# hybrid 2: XCD-wide re-alignment before P7 and before the next layer's in-proj (P9|P1), row-block seams elsewhere
# speedup vs baseline: 1.0051x; 1.0015x over previous
; __device__ __forceinline__ void xcd_barrier(const XcdBarrier& b) {
;     asm volatile("s_waitcnt vmcnt(0)" ::: "memory");
;     __syncthreads();
;     if (threadIdx.x == 0) {
;         unsigned* bar = b.bar;
;         __builtin_amdgcn_s_waitcnt(0);
;         unsigned nloc = b.st[0], nx = b.st[1];
;         if (nloc == 0u) { xcd_barrier_complete(bar, b.x, nloc, nx); b.st[0] = nloc; b.st[1] = nx; }
.LBB0_860:
	v_readlane_b32 s20, v255, 24
	s_add_i32 s20, s20, 8
	s_cmp_lt_i32 s20, s59
	s_cselect_b64 s[22:23], -1, 0
	s_and_b64 s[4:5], s[4:5], s[22:23]
	v_writelane_b32 v255, s20, 24
	s_andn2_b64 vcc, exec, s[4:5]
	s_cbranch_vccnz .LBB0_127
	s_waitcnt vmcnt(0)
	s_waitcnt vmcnt(0)
	s_barrier
	s_and_saveexec_b64 s[4:5], s[74:75]
	s_cbranch_execz .LBB0_126
	s_cmp_lg_u32 s100, 0
	s_cbranch_scc1 .Lgs_known_23337
	v_readlane_b32 s22, v255, 6
	v_readlane_b32 s23, v255, 7
	s_nop 4
	global_load_dword v6, v1, s[22:23] offset:1024 sc1
	global_load_dword v7, v1, s[22:23] offset:1088 sc1
	global_load_dword v8, v1, s[22:23] offset:1152 sc1
	global_load_dword v9, v1, s[22:23] offset:1216 sc1
	global_load_dword v10, v1, s[22:23] offset:1280 sc1
	global_load_dword v11, v1, s[22:23] offset:1344 sc1
	global_load_dword v12, v1, s[22:23] offset:1408 sc1
	global_load_dword v13, v1, s[22:23] offset:1472 sc1
	s_waitcnt vmcnt(0)
	v_add_u32_e32 v14, -1, v6
	v_and_b32_e32 v14, v14, v6
	v_add_u32_e32 v15, -1, v7
	v_and_b32_e32 v15, v15, v7
	v_or_b32_e32 v14, v14, v15
	v_add_u32_e32 v15, -1, v8
	v_and_b32_e32 v15, v15, v8
	v_or_b32_e32 v14, v14, v15
	v_add_u32_e32 v15, -1, v9
	v_and_b32_e32 v15, v15, v9
	v_or_b32_e32 v14, v14, v15
	v_add_u32_e32 v15, -1, v10
	v_and_b32_e32 v15, v15, v10
	v_or_b32_e32 v14, v14, v15
	v_add_u32_e32 v15, -1, v11
	v_and_b32_e32 v15, v15, v11
	v_or_b32_e32 v14, v14, v15
	v_add_u32_e32 v15, -1, v12
	v_and_b32_e32 v15, v15, v12
	v_or_b32_e32 v14, v14, v15
	v_add_u32_e32 v15, -1, v13
	v_and_b32_e32 v15, v15, v13
	v_or_b32_e32 v14, v14, v15
	s_nop 0
	v_readfirstlane_b32 s22, v14
	s_cmp_eq_u32 s22, 0
	s_cselect_b32 s100, 1, 2
.Lgs_known_23337:
	v_readlane_b32 s20, v255, 27
	s_waitcnt vmcnt(0) expcnt(0) lgkmcnt(0)
	s_nop 0
	v_mov_b32_e32 v0, s20
	ds_read_b32 v3, v0
	v_readlane_b32 s20, v255, 28
	s_waitcnt lgkmcnt(0)
	v_cmp_ne_u32_e32 vcc, 0, v3
	v_mov_b32_e32 v0, s20
	ds_read_b32 v2, v0
	s_cbranch_vccnz .LBB0_877
	v_readlane_b32 s26, v254, 0
	v_readlane_b32 s27, v254, 1
	s_load_dwordx2 s[22:23], s[26:27], 0x4
	s_waitcnt lgkmcnt(0)
	s_mul_i32 s20, s22, s3
	s_mul_i32 s20, s20, s23
	s_mov_b32 s22, 1
	s_branch .LBB0_865

; __device__ __forceinline__ unsigned xb_add(unsigned* p, unsigned v) { return __hip_atomic_fetch_add(p, v, __ATOMIC_RELAXED, __HIP_MEMORY_SCOPE_AGENT); }
; __device__ __forceinline__ void xcd_barrier(const XcdBarrier& b) {
;     ...
;         const unsigned old = xb_add(&bar[XB_XSUB(b.x)], 1u);
;         const unsigned gen = old / nloc;
;         if (old + 1u == (gen + 1u) * nloc) {
;             __builtin_amdgcn_fence(__ATOMIC_RELEASE, "agent");
;             asm volatile("s_waitcnt vmcnt(0)" ::: "memory");
;             const unsigned og = xb_add(&bar[XB_TOP], 1u);
.LBB0_893:
	s_andn2_saveexec_b64 s[22:23], s[26:27]
	s_cbranch_execz .LBB0_126
	s_mov_b64 s[26:27], exec
	s_cmp_eq_u32 s100, 1
	s_cbranch_scc1 .LBB0_910
	buffer_wbl2 sc1
	s_waitcnt lgkmcnt(0)
	s_waitcnt vmcnt(0)
	v_mbcnt_lo_u32_b32 v0, s26, 0
	v_mbcnt_hi_u32_b32 v0, s27, v0
	v_cmp_eq_u32_e32 vcc, 0, v0
	s_and_saveexec_b64 s[34:35], vcc
	s_cbranch_execz .LBB0_896
	s_bcnt1_i32_b64 s20, s[26:27]
	v_readlane_b32 s22, v255, 6
	v_mov_b32_e32 v3, s20
	v_readlane_b32 s23, v255, 7
	s_nop 4
	global_atomic_add v3, v1, v3, s[22:23] sc0
